# S5 final carry-in: unconditional chunk-end loads, 3 packed-f32 ops per complex step
# speedup vs baseline: 1.0017x; 1.0014x over previous
; template <bool FINAL>
; __device__ __forceinline__ void s5_wave(const Params& P, int j, int g, int idx0, int stride, char* ldsw) {
;     ...
;   for (int idx = idx0; idx < 16384; idx += stride) {
;   const int b = idx >> 11, chunk = ((idx >> 5) + 8 * b) & 63;
;   const size_t rowbase = (size_t)b * 4096 + chunk * 64;
;   const u16* up = Zo + (rowbase + lane) * 1280 + 768 + g * 16;
;   const uint4 u0 = *reinterpret_cast<const uint4*>(up);
;   const uint4 u1 = *reinterpret_cast<const uint4*>(up + 8);
;   float hr = 0.f, hi = 0.f;
;   if (FINAL) {
;     const float2* hp = hend + ((size_t)(b * 64) * 32 + g) * 64 + p;
;     int c = 0;
;     for (; c + 8 <= chunk; c += 8) {
;       float2 e[8];
; #pragma unroll
;       for (int q = 0; q < 8; ++q) e[q] = hp[(size_t)(c + q) * 2048];
; #pragma unroll
;       for (int q = 0; q < 8; ++q) {
;         float t_r = pr * hr - pi * hi + e[q].x;
;         float t_i = pr * hi + pi * hr + e[q].y;
;         hr = t_r; hi = t_i;
;       }
;     }
;     for (; c < chunk; ++c) {
;       float2 e = hp[(size_t)c * 2048];
;       float t_r = pr * hr - pi * hi + e.x;
;       float t_i = pr * hi + pi * hr + e.y;
;       hr = t_r; hi = t_i;
;     }
;   }
.LBB0_430:
	s_ashr_i32 s4, s2, 11
	s_lshr_b32 s0, s2, 5
	s_lshl_b32 s1, s4, 3
	s_add_i32 s1, s1, s0
	s_and_b32 s6, s1, 63
	s_ashr_i32 s5, s4, 31
	s_lshl_b64 s[0:1], s[4:5], 12
	s_lshl_b32 s5, s6, 6
	v_readlane_b32 s8, v253, 46
	s_or_b32 s0, s0, s5
	v_readlane_b32 s9, v253, 47
	s_lshl_b32 s4, s4, 6
	s_nop 0
	s_mul_i32 s7, s0, 0xa00
	s_add_u32 s10, s8, s7
	s_addc_u32 s11, s9, 0
	v_lshl_add_u64 v[234:235], v[110:111], 0, s[10:11]
	global_load_dwordx4 v[194:197], v[234:235], off offset:1536
	global_load_dwordx4 v[198:201], v[234:235], off offset:1552
	s_add_u32 s10, s10, 0x14000
	s_addc_u32 s11, s11, 0
	v_lshl_add_u64 v[234:235], v[110:111], 0, s[10:11]
	global_load_dwordx4 v[202:205], v[234:235], off offset:1536
	global_load_dwordx4 v[242:245], v[234:235], off offset:1552
	s_ashr_i32 s5, s4, 31
	s_lshl_b64 s[4:5], s[4:5], 14
	v_mov_b32_e32 v82, 0
	v_mov_b32_e32 v83, 0
	s_cmp_eq_u32 s6, 0
	s_cbranch_scc1 .Ls5f_cdone
	v_readfirstlane_b32 s14, v80
	v_readfirstlane_b32 s15, v81
	v_lshlrev_b32_e32 v109, 3, v48
	s_add_u32 s14, s14, s4
	s_addc_u32 s15, s15, s5
	global_load_dwordx2 v[116:117], v109, s[14:15]
	v_add_u32_e32 v109, 0x4000, v109
	global_load_dwordx2 v[118:119], v109, s[14:15]
	v_add_u32_e32 v109, 0x4000, v109
	global_load_dwordx2 v[120:121], v109, s[14:15]
	v_add_u32_e32 v109, 0x4000, v109
	global_load_dwordx2 v[122:123], v109, s[14:15]
	v_add_u32_e32 v109, 0x4000, v109
	global_load_dwordx2 v[124:125], v109, s[14:15]
	v_add_u32_e32 v109, 0x4000, v109
	global_load_dwordx2 v[126:127], v109, s[14:15]
	v_add_u32_e32 v109, 0x4000, v109
	global_load_dwordx2 v[128:129], v109, s[14:15]
	v_add_u32_e32 v109, 0x4000, v109
	global_load_dwordx2 v[130:131], v109, s[14:15]
	v_add_u32_e32 v109, 0x4000, v109
	global_load_dwordx2 v[132:133], v109, s[14:15]
	v_add_u32_e32 v109, 0x4000, v109
	global_load_dwordx2 v[134:135], v109, s[14:15]
	v_add_u32_e32 v109, 0x4000, v109
	global_load_dwordx2 v[136:137], v109, s[14:15]
	v_add_u32_e32 v109, 0x4000, v109
	global_load_dwordx2 v[138:139], v109, s[14:15]
	v_add_u32_e32 v109, 0x4000, v109
	global_load_dwordx2 v[140:141], v109, s[14:15]
	v_add_u32_e32 v109, 0x4000, v109
	global_load_dwordx2 v[142:143], v109, s[14:15]
	v_add_u32_e32 v109, 0x4000, v109
	global_load_dwordx2 v[144:145], v109, s[14:15]
	v_add_u32_e32 v109, 0x4000, v109
	global_load_dwordx2 v[146:147], v109, s[14:15]
	v_add_u32_e32 v109, 0x4000, v109
	global_load_dwordx2 v[148:149], v109, s[14:15]
	v_add_u32_e32 v109, 0x4000, v109
	global_load_dwordx2 v[150:151], v109, s[14:15]
	v_add_u32_e32 v109, 0x4000, v109
	global_load_dwordx2 v[152:153], v109, s[14:15]
	v_add_u32_e32 v109, 0x4000, v109
	global_load_dwordx2 v[154:155], v109, s[14:15]
	v_add_u32_e32 v109, 0x4000, v109
	global_load_dwordx2 v[156:157], v109, s[14:15]
	v_add_u32_e32 v109, 0x4000, v109
	global_load_dwordx2 v[158:159], v109, s[14:15]
	v_add_u32_e32 v109, 0x4000, v109
	global_load_dwordx2 v[160:161], v109, s[14:15]
	v_add_u32_e32 v109, 0x4000, v109
	global_load_dwordx2 v[162:163], v109, s[14:15]
	v_add_u32_e32 v109, 0x4000, v109
	global_load_dwordx2 v[164:165], v109, s[14:15]
	v_add_u32_e32 v109, 0x4000, v109
	global_load_dwordx2 v[166:167], v109, s[14:15]
	v_add_u32_e32 v109, 0x4000, v109
	global_load_dwordx2 v[168:169], v109, s[14:15]
	v_add_u32_e32 v109, 0x4000, v109
	global_load_dwordx2 v[170:171], v109, s[14:15]
	v_add_u32_e32 v109, 0x4000, v109
	global_load_dwordx2 v[172:173], v109, s[14:15]
	v_add_u32_e32 v109, 0x4000, v109
	global_load_dwordx2 v[174:175], v109, s[14:15]
	v_add_u32_e32 v109, 0x4000, v109
	global_load_dwordx2 v[176:177], v109, s[14:15]
	v_add_u32_e32 v109, 0x4000, v109
	global_load_dwordx2 v[178:179], v109, s[14:15]
	v_add_u32_e32 v109, 0x4000, v109
	s_waitcnt vmcnt(0)
	s_cmp_gt_u32 s6, 0
	s_cselect_b64 exec, -1, 0
	v_pk_mul_f32 v[100:101], v[74:75], v[82:83] op_sel:[0,1] op_sel_hi:[1,0]
	v_pk_fma_f32 v[116:117], v[72:73], v[82:83], v[116:117]
	v_pk_add_f32 v[82:83], v[116:117], v[100:101] neg_lo:[0,1]
	s_cmp_gt_u32 s6, 1
	s_cselect_b64 exec, -1, 0
	v_pk_mul_f32 v[100:101], v[74:75], v[82:83] op_sel:[0,1] op_sel_hi:[1,0]
	v_pk_fma_f32 v[118:119], v[72:73], v[82:83], v[118:119]
	v_pk_add_f32 v[82:83], v[118:119], v[100:101] neg_lo:[0,1]
	s_cmp_gt_u32 s6, 2
	s_cselect_b64 exec, -1, 0
	v_pk_mul_f32 v[100:101], v[74:75], v[82:83] op_sel:[0,1] op_sel_hi:[1,0]
	v_pk_fma_f32 v[120:121], v[72:73], v[82:83], v[120:121]
	v_pk_add_f32 v[82:83], v[120:121], v[100:101] neg_lo:[0,1]
	s_cmp_gt_u32 s6, 3
	s_cselect_b64 exec, -1, 0
	v_pk_mul_f32 v[100:101], v[74:75], v[82:83] op_sel:[0,1] op_sel_hi:[1,0]
	v_pk_fma_f32 v[122:123], v[72:73], v[82:83], v[122:123]
	v_pk_add_f32 v[82:83], v[122:123], v[100:101] neg_lo:[0,1]
	s_cmp_gt_u32 s6, 4
	s_cselect_b64 exec, -1, 0
	v_pk_mul_f32 v[100:101], v[74:75], v[82:83] op_sel:[0,1] op_sel_hi:[1,0]
	v_pk_fma_f32 v[124:125], v[72:73], v[82:83], v[124:125]
	v_pk_add_f32 v[82:83], v[124:125], v[100:101] neg_lo:[0,1]
	s_cmp_gt_u32 s6, 5
	s_cselect_b64 exec, -1, 0
	v_pk_mul_f32 v[100:101], v[74:75], v[82:83] op_sel:[0,1] op_sel_hi:[1,0]
	v_pk_fma_f32 v[126:127], v[72:73], v[82:83], v[126:127]
	v_pk_add_f32 v[82:83], v[126:127], v[100:101] neg_lo:[0,1]
	s_cmp_gt_u32 s6, 6
	s_cselect_b64 exec, -1, 0
	v_pk_mul_f32 v[100:101], v[74:75], v[82:83] op_sel:[0,1] op_sel_hi:[1,0]
	v_pk_fma_f32 v[128:129], v[72:73], v[82:83], v[128:129]
	v_pk_add_f32 v[82:83], v[128:129], v[100:101] neg_lo:[0,1]
	s_cmp_gt_u32 s6, 7
	s_cselect_b64 exec, -1, 0
	v_pk_mul_f32 v[100:101], v[74:75], v[82:83] op_sel:[0,1] op_sel_hi:[1,0]
	v_pk_fma_f32 v[130:131], v[72:73], v[82:83], v[130:131]
	v_pk_add_f32 v[82:83], v[130:131], v[100:101] neg_lo:[0,1]
	s_cmp_le_u32 s6, 8
	s_cbranch_scc1 .Ls5f_cdone
; template <bool FINAL>
; __device__ __forceinline__ void s5_wave(const Params& P, int j, int g, int idx0, int stride, char* ldsw) {
;     ...
;     int c = 0;
;     for (; c + 8 <= chunk; c += 8) {
;       float2 e[8];
; #pragma unroll
;       for (int q = 0; q < 8; ++q) e[q] = hp[(size_t)(c + q) * 2048];
; #pragma unroll
;       for (int q = 0; q < 8; ++q) {
;         float t_r = pr * hr - pi * hi + e[q].x;
;         float t_i = pr * hi + pi * hr + e[q].y;
;         hr = t_r; hi = t_i;
;       }
;     }
	s_cmp_gt_u32 s6, 8
	s_cselect_b64 exec, -1, 0
	v_pk_mul_f32 v[100:101], v[74:75], v[82:83] op_sel:[0,1] op_sel_hi:[1,0]
	v_pk_fma_f32 v[132:133], v[72:73], v[82:83], v[132:133]
	v_pk_add_f32 v[82:83], v[132:133], v[100:101] neg_lo:[0,1]
	s_cmp_gt_u32 s6, 9
	s_cselect_b64 exec, -1, 0
	v_pk_mul_f32 v[100:101], v[74:75], v[82:83] op_sel:[0,1] op_sel_hi:[1,0]
	v_pk_fma_f32 v[134:135], v[72:73], v[82:83], v[134:135]
	v_pk_add_f32 v[82:83], v[134:135], v[100:101] neg_lo:[0,1]
	s_cmp_gt_u32 s6, 10
	s_cselect_b64 exec, -1, 0
	v_pk_mul_f32 v[100:101], v[74:75], v[82:83] op_sel:[0,1] op_sel_hi:[1,0]
	v_pk_fma_f32 v[136:137], v[72:73], v[82:83], v[136:137]
	v_pk_add_f32 v[82:83], v[136:137], v[100:101] neg_lo:[0,1]
	s_cmp_gt_u32 s6, 11
	s_cselect_b64 exec, -1, 0
	v_pk_mul_f32 v[100:101], v[74:75], v[82:83] op_sel:[0,1] op_sel_hi:[1,0]
	v_pk_fma_f32 v[138:139], v[72:73], v[82:83], v[138:139]
	v_pk_add_f32 v[82:83], v[138:139], v[100:101] neg_lo:[0,1]
	s_cmp_gt_u32 s6, 12
	s_cselect_b64 exec, -1, 0
	v_pk_mul_f32 v[100:101], v[74:75], v[82:83] op_sel:[0,1] op_sel_hi:[1,0]
	v_pk_fma_f32 v[140:141], v[72:73], v[82:83], v[140:141]
	v_pk_add_f32 v[82:83], v[140:141], v[100:101] neg_lo:[0,1]
	s_cmp_gt_u32 s6, 13
	s_cselect_b64 exec, -1, 0
	v_pk_mul_f32 v[100:101], v[74:75], v[82:83] op_sel:[0,1] op_sel_hi:[1,0]
	v_pk_fma_f32 v[142:143], v[72:73], v[82:83], v[142:143]
	v_pk_add_f32 v[82:83], v[142:143], v[100:101] neg_lo:[0,1]
	s_cmp_gt_u32 s6, 14
	s_cselect_b64 exec, -1, 0
	v_pk_mul_f32 v[100:101], v[74:75], v[82:83] op_sel:[0,1] op_sel_hi:[1,0]
	v_pk_fma_f32 v[144:145], v[72:73], v[82:83], v[144:145]
	v_pk_add_f32 v[82:83], v[144:145], v[100:101] neg_lo:[0,1]
	s_cmp_gt_u32 s6, 15
	s_cselect_b64 exec, -1, 0
	v_pk_mul_f32 v[100:101], v[74:75], v[82:83] op_sel:[0,1] op_sel_hi:[1,0]
	v_pk_fma_f32 v[146:147], v[72:73], v[82:83], v[146:147]
	v_pk_add_f32 v[82:83], v[146:147], v[100:101] neg_lo:[0,1]
	s_cmp_le_u32 s6, 16
	s_cbranch_scc1 .Ls5f_cdone
	s_cmp_gt_u32 s6, 16
	s_cselect_b64 exec, -1, 0
	v_pk_mul_f32 v[100:101], v[74:75], v[82:83] op_sel:[0,1] op_sel_hi:[1,0]
	v_pk_fma_f32 v[148:149], v[72:73], v[82:83], v[148:149]
	v_pk_add_f32 v[82:83], v[148:149], v[100:101] neg_lo:[0,1]
	s_cmp_gt_u32 s6, 17
	s_cselect_b64 exec, -1, 0
	v_pk_mul_f32 v[100:101], v[74:75], v[82:83] op_sel:[0,1] op_sel_hi:[1,0]
	v_pk_fma_f32 v[150:151], v[72:73], v[82:83], v[150:151]
	v_pk_add_f32 v[82:83], v[150:151], v[100:101] neg_lo:[0,1]
	s_cmp_gt_u32 s6, 18
	s_cselect_b64 exec, -1, 0
	v_pk_mul_f32 v[100:101], v[74:75], v[82:83] op_sel:[0,1] op_sel_hi:[1,0]
	v_pk_fma_f32 v[152:153], v[72:73], v[82:83], v[152:153]
	v_pk_add_f32 v[82:83], v[152:153], v[100:101] neg_lo:[0,1]
	s_cmp_gt_u32 s6, 19
	s_cselect_b64 exec, -1, 0
	v_pk_mul_f32 v[100:101], v[74:75], v[82:83] op_sel:[0,1] op_sel_hi:[1,0]
	v_pk_fma_f32 v[154:155], v[72:73], v[82:83], v[154:155]
	v_pk_add_f32 v[82:83], v[154:155], v[100:101] neg_lo:[0,1]
	s_cmp_gt_u32 s6, 20
	s_cselect_b64 exec, -1, 0
	v_pk_mul_f32 v[100:101], v[74:75], v[82:83] op_sel:[0,1] op_sel_hi:[1,0]
	v_pk_fma_f32 v[156:157], v[72:73], v[82:83], v[156:157]
	v_pk_add_f32 v[82:83], v[156:157], v[100:101] neg_lo:[0,1]
	s_cmp_gt_u32 s6, 21
	s_cselect_b64 exec, -1, 0
	v_pk_mul_f32 v[100:101], v[74:75], v[82:83] op_sel:[0,1] op_sel_hi:[1,0]
	v_pk_fma_f32 v[158:159], v[72:73], v[82:83], v[158:159]
	v_pk_add_f32 v[82:83], v[158:159], v[100:101] neg_lo:[0,1]
	s_cmp_gt_u32 s6, 22
	s_cselect_b64 exec, -1, 0
	v_pk_mul_f32 v[100:101], v[74:75], v[82:83] op_sel:[0,1] op_sel_hi:[1,0]
	v_pk_fma_f32 v[160:161], v[72:73], v[82:83], v[160:161]
	v_pk_add_f32 v[82:83], v[160:161], v[100:101] neg_lo:[0,1]
	s_cmp_gt_u32 s6, 23
	s_cselect_b64 exec, -1, 0
	v_pk_mul_f32 v[100:101], v[74:75], v[82:83] op_sel:[0,1] op_sel_hi:[1,0]
	v_pk_fma_f32 v[162:163], v[72:73], v[82:83], v[162:163]
	v_pk_add_f32 v[82:83], v[162:163], v[100:101] neg_lo:[0,1]
	s_cmp_le_u32 s6, 24
	s_cbranch_scc1 .Ls5f_cdone
	s_cmp_gt_u32 s6, 24
	s_cselect_b64 exec, -1, 0
	v_pk_mul_f32 v[100:101], v[74:75], v[82:83] op_sel:[0,1] op_sel_hi:[1,0]
	v_pk_fma_f32 v[164:165], v[72:73], v[82:83], v[164:165]
	v_pk_add_f32 v[82:83], v[164:165], v[100:101] neg_lo:[0,1]
	s_cmp_gt_u32 s6, 25
	s_cselect_b64 exec, -1, 0
	v_pk_mul_f32 v[100:101], v[74:75], v[82:83] op_sel:[0,1] op_sel_hi:[1,0]
	v_pk_fma_f32 v[166:167], v[72:73], v[82:83], v[166:167]
	v_pk_add_f32 v[82:83], v[166:167], v[100:101] neg_lo:[0,1]
	s_cmp_gt_u32 s6, 26
	s_cselect_b64 exec, -1, 0
	v_pk_mul_f32 v[100:101], v[74:75], v[82:83] op_sel:[0,1] op_sel_hi:[1,0]
	v_pk_fma_f32 v[168:169], v[72:73], v[82:83], v[168:169]
	v_pk_add_f32 v[82:83], v[168:169], v[100:101] neg_lo:[0,1]
	s_cmp_gt_u32 s6, 27
	s_cselect_b64 exec, -1, 0
	v_pk_mul_f32 v[100:101], v[74:75], v[82:83] op_sel:[0,1] op_sel_hi:[1,0]
	v_pk_fma_f32 v[170:171], v[72:73], v[82:83], v[170:171]
	v_pk_add_f32 v[82:83], v[170:171], v[100:101] neg_lo:[0,1]
	s_cmp_gt_u32 s6, 28
	s_cselect_b64 exec, -1, 0
	v_pk_mul_f32 v[100:101], v[74:75], v[82:83] op_sel:[0,1] op_sel_hi:[1,0]
	v_pk_fma_f32 v[172:173], v[72:73], v[82:83], v[172:173]
	v_pk_add_f32 v[82:83], v[172:173], v[100:101] neg_lo:[0,1]
	s_cmp_gt_u32 s6, 29
	s_cselect_b64 exec, -1, 0
	v_pk_mul_f32 v[100:101], v[74:75], v[82:83] op_sel:[0,1] op_sel_hi:[1,0]
	v_pk_fma_f32 v[174:175], v[72:73], v[82:83], v[174:175]
	v_pk_add_f32 v[82:83], v[174:175], v[100:101] neg_lo:[0,1]
	s_cmp_gt_u32 s6, 30
	s_cselect_b64 exec, -1, 0
	v_pk_mul_f32 v[100:101], v[74:75], v[82:83] op_sel:[0,1] op_sel_hi:[1,0]
	v_pk_fma_f32 v[176:177], v[72:73], v[82:83], v[176:177]
	v_pk_add_f32 v[82:83], v[176:177], v[100:101] neg_lo:[0,1]
	s_cmp_gt_u32 s6, 31
	s_cselect_b64 exec, -1, 0
	v_pk_mul_f32 v[100:101], v[74:75], v[82:83] op_sel:[0,1] op_sel_hi:[1,0]
	v_pk_fma_f32 v[178:179], v[72:73], v[82:83], v[178:179]
	v_pk_add_f32 v[82:83], v[178:179], v[100:101] neg_lo:[0,1]
	s_cmp_le_u32 s6, 32
	s_cbranch_scc1 .Ls5f_cdone
; template <bool FINAL>
; __device__ __forceinline__ void s5_wave(const Params& P, int j, int g, int idx0, int stride, char* ldsw) {
;     ...
;     int c = 0;
;     for (; c + 8 <= chunk; c += 8) {
;       float2 e[8];
; #pragma unroll
;       for (int q = 0; q < 8; ++q) e[q] = hp[(size_t)(c + q) * 2048];
; #pragma unroll
;       for (int q = 0; q < 8; ++q) {
;         float t_r = pr * hr - pi * hi + e[q].x;
;         float t_i = pr * hi + pi * hr + e[q].y;
;         hr = t_r; hi = t_i;
;       }
;     }
;     for (; c < chunk; ++c) {
;       float2 e = hp[(size_t)c * 2048];
;       float t_r = pr * hr - pi * hi + e.x;
;       float t_i = pr * hi + pi * hr + e.y;
;       hr = t_r; hi = t_i;
;     }
;   }
	global_load_dwordx2 v[116:117], v109, s[14:15]
	v_add_u32_e32 v109, 0x4000, v109
	global_load_dwordx2 v[118:119], v109, s[14:15]
	v_add_u32_e32 v109, 0x4000, v109
	global_load_dwordx2 v[120:121], v109, s[14:15]
	v_add_u32_e32 v109, 0x4000, v109
	global_load_dwordx2 v[122:123], v109, s[14:15]
	v_add_u32_e32 v109, 0x4000, v109
	global_load_dwordx2 v[124:125], v109, s[14:15]
	v_add_u32_e32 v109, 0x4000, v109
	global_load_dwordx2 v[126:127], v109, s[14:15]
	v_add_u32_e32 v109, 0x4000, v109
	global_load_dwordx2 v[128:129], v109, s[14:15]
	v_add_u32_e32 v109, 0x4000, v109
	global_load_dwordx2 v[130:131], v109, s[14:15]
	v_add_u32_e32 v109, 0x4000, v109
	global_load_dwordx2 v[132:133], v109, s[14:15]
	v_add_u32_e32 v109, 0x4000, v109
	global_load_dwordx2 v[134:135], v109, s[14:15]
	v_add_u32_e32 v109, 0x4000, v109
	global_load_dwordx2 v[136:137], v109, s[14:15]
	v_add_u32_e32 v109, 0x4000, v109
	global_load_dwordx2 v[138:139], v109, s[14:15]
	v_add_u32_e32 v109, 0x4000, v109
	global_load_dwordx2 v[140:141], v109, s[14:15]
	v_add_u32_e32 v109, 0x4000, v109
	global_load_dwordx2 v[142:143], v109, s[14:15]
	v_add_u32_e32 v109, 0x4000, v109
	global_load_dwordx2 v[144:145], v109, s[14:15]
	v_add_u32_e32 v109, 0x4000, v109
	global_load_dwordx2 v[146:147], v109, s[14:15]
	v_add_u32_e32 v109, 0x4000, v109
	global_load_dwordx2 v[148:149], v109, s[14:15]
	v_add_u32_e32 v109, 0x4000, v109
	global_load_dwordx2 v[150:151], v109, s[14:15]
	v_add_u32_e32 v109, 0x4000, v109
	global_load_dwordx2 v[152:153], v109, s[14:15]
	v_add_u32_e32 v109, 0x4000, v109
	global_load_dwordx2 v[154:155], v109, s[14:15]
	v_add_u32_e32 v109, 0x4000, v109
	global_load_dwordx2 v[156:157], v109, s[14:15]
	v_add_u32_e32 v109, 0x4000, v109
	global_load_dwordx2 v[158:159], v109, s[14:15]
	v_add_u32_e32 v109, 0x4000, v109
	global_load_dwordx2 v[160:161], v109, s[14:15]
	v_add_u32_e32 v109, 0x4000, v109
	global_load_dwordx2 v[162:163], v109, s[14:15]
	v_add_u32_e32 v109, 0x4000, v109
	global_load_dwordx2 v[164:165], v109, s[14:15]
	v_add_u32_e32 v109, 0x4000, v109
	global_load_dwordx2 v[166:167], v109, s[14:15]
	v_add_u32_e32 v109, 0x4000, v109
	global_load_dwordx2 v[168:169], v109, s[14:15]
	v_add_u32_e32 v109, 0x4000, v109
	global_load_dwordx2 v[170:171], v109, s[14:15]
	v_add_u32_e32 v109, 0x4000, v109
	global_load_dwordx2 v[172:173], v109, s[14:15]
	v_add_u32_e32 v109, 0x4000, v109
	global_load_dwordx2 v[174:175], v109, s[14:15]
	v_add_u32_e32 v109, 0x4000, v109
	global_load_dwordx2 v[176:177], v109, s[14:15]
	v_add_u32_e32 v109, 0x4000, v109
	global_load_dwordx2 v[178:179], v109, s[14:15]
	v_add_u32_e32 v109, 0x4000, v109
	s_waitcnt vmcnt(0)
	s_cmp_gt_u32 s6, 32
	s_cselect_b64 exec, -1, 0
	v_pk_mul_f32 v[100:101], v[74:75], v[82:83] op_sel:[0,1] op_sel_hi:[1,0]
	v_pk_fma_f32 v[116:117], v[72:73], v[82:83], v[116:117]
	v_pk_add_f32 v[82:83], v[116:117], v[100:101] neg_lo:[0,1]
	s_cmp_gt_u32 s6, 33
	s_cselect_b64 exec, -1, 0
	v_pk_mul_f32 v[100:101], v[74:75], v[82:83] op_sel:[0,1] op_sel_hi:[1,0]
	v_pk_fma_f32 v[118:119], v[72:73], v[82:83], v[118:119]
	v_pk_add_f32 v[82:83], v[118:119], v[100:101] neg_lo:[0,1]
	s_cmp_gt_u32 s6, 34
	s_cselect_b64 exec, -1, 0
	v_pk_mul_f32 v[100:101], v[74:75], v[82:83] op_sel:[0,1] op_sel_hi:[1,0]
	v_pk_fma_f32 v[120:121], v[72:73], v[82:83], v[120:121]
	v_pk_add_f32 v[82:83], v[120:121], v[100:101] neg_lo:[0,1]
	s_cmp_gt_u32 s6, 35
	s_cselect_b64 exec, -1, 0
	v_pk_mul_f32 v[100:101], v[74:75], v[82:83] op_sel:[0,1] op_sel_hi:[1,0]
	v_pk_fma_f32 v[122:123], v[72:73], v[82:83], v[122:123]
	v_pk_add_f32 v[82:83], v[122:123], v[100:101] neg_lo:[0,1]
	s_cmp_gt_u32 s6, 36
	s_cselect_b64 exec, -1, 0
	v_pk_mul_f32 v[100:101], v[74:75], v[82:83] op_sel:[0,1] op_sel_hi:[1,0]
	v_pk_fma_f32 v[124:125], v[72:73], v[82:83], v[124:125]
	v_pk_add_f32 v[82:83], v[124:125], v[100:101] neg_lo:[0,1]
	s_cmp_gt_u32 s6, 37
	s_cselect_b64 exec, -1, 0
	v_pk_mul_f32 v[100:101], v[74:75], v[82:83] op_sel:[0,1] op_sel_hi:[1,0]
	v_pk_fma_f32 v[126:127], v[72:73], v[82:83], v[126:127]
	v_pk_add_f32 v[82:83], v[126:127], v[100:101] neg_lo:[0,1]
	s_cmp_gt_u32 s6, 38
	s_cselect_b64 exec, -1, 0
	v_pk_mul_f32 v[100:101], v[74:75], v[82:83] op_sel:[0,1] op_sel_hi:[1,0]
	v_pk_fma_f32 v[128:129], v[72:73], v[82:83], v[128:129]
	v_pk_add_f32 v[82:83], v[128:129], v[100:101] neg_lo:[0,1]
	s_cmp_gt_u32 s6, 39
	s_cselect_b64 exec, -1, 0
	v_pk_mul_f32 v[100:101], v[74:75], v[82:83] op_sel:[0,1] op_sel_hi:[1,0]
	v_pk_fma_f32 v[130:131], v[72:73], v[82:83], v[130:131]
	v_pk_add_f32 v[82:83], v[130:131], v[100:101] neg_lo:[0,1]
	s_cmp_le_u32 s6, 40
	s_cbranch_scc1 .Ls5f_cdone
; template <bool FINAL>
; __device__ __forceinline__ void s5_wave(const Params& P, int j, int g, int idx0, int stride, char* ldsw) {
;     ...
;     int c = 0;
;     for (; c + 8 <= chunk; c += 8) {
;       float2 e[8];
; #pragma unroll
;       for (int q = 0; q < 8; ++q) e[q] = hp[(size_t)(c + q) * 2048];
; #pragma unroll
;       for (int q = 0; q < 8; ++q) {
;         float t_r = pr * hr - pi * hi + e[q].x;
;         float t_i = pr * hi + pi * hr + e[q].y;
;         hr = t_r; hi = t_i;
;       }
;     }
;     for (; c < chunk; ++c) {
;       float2 e = hp[(size_t)c * 2048];
;       float t_r = pr * hr - pi * hi + e.x;
;       float t_i = pr * hi + pi * hr + e.y;
;       hr = t_r; hi = t_i;
;     }
;   }
	s_cmp_gt_u32 s6, 40
	s_cselect_b64 exec, -1, 0
	v_pk_mul_f32 v[100:101], v[74:75], v[82:83] op_sel:[0,1] op_sel_hi:[1,0]
	v_pk_fma_f32 v[132:133], v[72:73], v[82:83], v[132:133]
	v_pk_add_f32 v[82:83], v[132:133], v[100:101] neg_lo:[0,1]
	s_cmp_gt_u32 s6, 41
	s_cselect_b64 exec, -1, 0
	v_pk_mul_f32 v[100:101], v[74:75], v[82:83] op_sel:[0,1] op_sel_hi:[1,0]
	v_pk_fma_f32 v[134:135], v[72:73], v[82:83], v[134:135]
	v_pk_add_f32 v[82:83], v[134:135], v[100:101] neg_lo:[0,1]
	s_cmp_gt_u32 s6, 42
	s_cselect_b64 exec, -1, 0
	v_pk_mul_f32 v[100:101], v[74:75], v[82:83] op_sel:[0,1] op_sel_hi:[1,0]
	v_pk_fma_f32 v[136:137], v[72:73], v[82:83], v[136:137]
	v_pk_add_f32 v[82:83], v[136:137], v[100:101] neg_lo:[0,1]
	s_cmp_gt_u32 s6, 43
	s_cselect_b64 exec, -1, 0
	v_pk_mul_f32 v[100:101], v[74:75], v[82:83] op_sel:[0,1] op_sel_hi:[1,0]
	v_pk_fma_f32 v[138:139], v[72:73], v[82:83], v[138:139]
	v_pk_add_f32 v[82:83], v[138:139], v[100:101] neg_lo:[0,1]
	s_cmp_gt_u32 s6, 44
	s_cselect_b64 exec, -1, 0
	v_pk_mul_f32 v[100:101], v[74:75], v[82:83] op_sel:[0,1] op_sel_hi:[1,0]
	v_pk_fma_f32 v[140:141], v[72:73], v[82:83], v[140:141]
	v_pk_add_f32 v[82:83], v[140:141], v[100:101] neg_lo:[0,1]
	s_cmp_gt_u32 s6, 45
	s_cselect_b64 exec, -1, 0
	v_pk_mul_f32 v[100:101], v[74:75], v[82:83] op_sel:[0,1] op_sel_hi:[1,0]
	v_pk_fma_f32 v[142:143], v[72:73], v[82:83], v[142:143]
	v_pk_add_f32 v[82:83], v[142:143], v[100:101] neg_lo:[0,1]
	s_cmp_gt_u32 s6, 46
	s_cselect_b64 exec, -1, 0
	v_pk_mul_f32 v[100:101], v[74:75], v[82:83] op_sel:[0,1] op_sel_hi:[1,0]
	v_pk_fma_f32 v[144:145], v[72:73], v[82:83], v[144:145]
	v_pk_add_f32 v[82:83], v[144:145], v[100:101] neg_lo:[0,1]
	s_cmp_gt_u32 s6, 47
	s_cselect_b64 exec, -1, 0
	v_pk_mul_f32 v[100:101], v[74:75], v[82:83] op_sel:[0,1] op_sel_hi:[1,0]
	v_pk_fma_f32 v[146:147], v[72:73], v[82:83], v[146:147]
	v_pk_add_f32 v[82:83], v[146:147], v[100:101] neg_lo:[0,1]
	s_cmp_le_u32 s6, 48
	s_cbranch_scc1 .Ls5f_cdone
	s_cmp_gt_u32 s6, 48
	s_cselect_b64 exec, -1, 0
	v_pk_mul_f32 v[100:101], v[74:75], v[82:83] op_sel:[0,1] op_sel_hi:[1,0]
	v_pk_fma_f32 v[148:149], v[72:73], v[82:83], v[148:149]
	v_pk_add_f32 v[82:83], v[148:149], v[100:101] neg_lo:[0,1]
	s_cmp_gt_u32 s6, 49
	s_cselect_b64 exec, -1, 0
	v_pk_mul_f32 v[100:101], v[74:75], v[82:83] op_sel:[0,1] op_sel_hi:[1,0]
	v_pk_fma_f32 v[150:151], v[72:73], v[82:83], v[150:151]
	v_pk_add_f32 v[82:83], v[150:151], v[100:101] neg_lo:[0,1]
	s_cmp_gt_u32 s6, 50
	s_cselect_b64 exec, -1, 0
	v_pk_mul_f32 v[100:101], v[74:75], v[82:83] op_sel:[0,1] op_sel_hi:[1,0]
	v_pk_fma_f32 v[152:153], v[72:73], v[82:83], v[152:153]
	v_pk_add_f32 v[82:83], v[152:153], v[100:101] neg_lo:[0,1]
	s_cmp_gt_u32 s6, 51
	s_cselect_b64 exec, -1, 0
	v_pk_mul_f32 v[100:101], v[74:75], v[82:83] op_sel:[0,1] op_sel_hi:[1,0]
	v_pk_fma_f32 v[154:155], v[72:73], v[82:83], v[154:155]
	v_pk_add_f32 v[82:83], v[154:155], v[100:101] neg_lo:[0,1]
	s_cmp_gt_u32 s6, 52
	s_cselect_b64 exec, -1, 0
	v_pk_mul_f32 v[100:101], v[74:75], v[82:83] op_sel:[0,1] op_sel_hi:[1,0]
	v_pk_fma_f32 v[156:157], v[72:73], v[82:83], v[156:157]
	v_pk_add_f32 v[82:83], v[156:157], v[100:101] neg_lo:[0,1]
	s_cmp_gt_u32 s6, 53
	s_cselect_b64 exec, -1, 0
	v_pk_mul_f32 v[100:101], v[74:75], v[82:83] op_sel:[0,1] op_sel_hi:[1,0]
	v_pk_fma_f32 v[158:159], v[72:73], v[82:83], v[158:159]
	v_pk_add_f32 v[82:83], v[158:159], v[100:101] neg_lo:[0,1]
	s_cmp_gt_u32 s6, 54
	s_cselect_b64 exec, -1, 0
	v_pk_mul_f32 v[100:101], v[74:75], v[82:83] op_sel:[0,1] op_sel_hi:[1,0]
	v_pk_fma_f32 v[160:161], v[72:73], v[82:83], v[160:161]
	v_pk_add_f32 v[82:83], v[160:161], v[100:101] neg_lo:[0,1]
	s_cmp_gt_u32 s6, 55
	s_cselect_b64 exec, -1, 0
	v_pk_mul_f32 v[100:101], v[74:75], v[82:83] op_sel:[0,1] op_sel_hi:[1,0]
	v_pk_fma_f32 v[162:163], v[72:73], v[82:83], v[162:163]
	v_pk_add_f32 v[82:83], v[162:163], v[100:101] neg_lo:[0,1]
	s_cmp_le_u32 s6, 56
	s_cbranch_scc1 .Ls5f_cdone
	s_cmp_gt_u32 s6, 56
	s_cselect_b64 exec, -1, 0
	v_pk_mul_f32 v[100:101], v[74:75], v[82:83] op_sel:[0,1] op_sel_hi:[1,0]
	v_pk_fma_f32 v[164:165], v[72:73], v[82:83], v[164:165]
	v_pk_add_f32 v[82:83], v[164:165], v[100:101] neg_lo:[0,1]
	s_cmp_gt_u32 s6, 57
	s_cselect_b64 exec, -1, 0
	v_pk_mul_f32 v[100:101], v[74:75], v[82:83] op_sel:[0,1] op_sel_hi:[1,0]
	v_pk_fma_f32 v[166:167], v[72:73], v[82:83], v[166:167]
	v_pk_add_f32 v[82:83], v[166:167], v[100:101] neg_lo:[0,1]
	s_cmp_gt_u32 s6, 58
	s_cselect_b64 exec, -1, 0
	v_pk_mul_f32 v[100:101], v[74:75], v[82:83] op_sel:[0,1] op_sel_hi:[1,0]
	v_pk_fma_f32 v[168:169], v[72:73], v[82:83], v[168:169]
	v_pk_add_f32 v[82:83], v[168:169], v[100:101] neg_lo:[0,1]
	s_cmp_gt_u32 s6, 59
	s_cselect_b64 exec, -1, 0
	v_pk_mul_f32 v[100:101], v[74:75], v[82:83] op_sel:[0,1] op_sel_hi:[1,0]
	v_pk_fma_f32 v[170:171], v[72:73], v[82:83], v[170:171]
	v_pk_add_f32 v[82:83], v[170:171], v[100:101] neg_lo:[0,1]
	s_cmp_gt_u32 s6, 60
	s_cselect_b64 exec, -1, 0
	v_pk_mul_f32 v[100:101], v[74:75], v[82:83] op_sel:[0,1] op_sel_hi:[1,0]
	v_pk_fma_f32 v[172:173], v[72:73], v[82:83], v[172:173]
	v_pk_add_f32 v[82:83], v[172:173], v[100:101] neg_lo:[0,1]
	s_cmp_gt_u32 s6, 61
	s_cselect_b64 exec, -1, 0
	v_pk_mul_f32 v[100:101], v[74:75], v[82:83] op_sel:[0,1] op_sel_hi:[1,0]
	v_pk_fma_f32 v[174:175], v[72:73], v[82:83], v[174:175]
	v_pk_add_f32 v[82:83], v[174:175], v[100:101] neg_lo:[0,1]
	s_cmp_gt_u32 s6, 62
	s_cselect_b64 exec, -1, 0
	v_pk_mul_f32 v[100:101], v[74:75], v[82:83] op_sel:[0,1] op_sel_hi:[1,0]
	v_pk_fma_f32 v[176:177], v[72:73], v[82:83], v[176:177]
	v_pk_add_f32 v[82:83], v[176:177], v[100:101] neg_lo:[0,1]
	s_cmp_gt_u32 s6, 63
	s_cselect_b64 exec, -1, 0
	v_pk_mul_f32 v[100:101], v[74:75], v[82:83] op_sel:[0,1] op_sel_hi:[1,0]
	v_pk_fma_f32 v[178:179], v[72:73], v[82:83], v[178:179]
	v_pk_add_f32 v[82:83], v[178:179], v[100:101] neg_lo:[0,1]
